# arrival atomic and invalidate issued before the census words come back from LDS (atomic-first arrival) on the all-to-all release version
# speedup vs baseline: 1.0039x; 1.0039x over previous
; __device__ __forceinline__ unsigned xb_ld(unsigned* p)              { return __hip_atomic_load(p, __ATOMIC_RELAXED, __HIP_MEMORY_SCOPE_AGENT); }
; __device__ __forceinline__ unsigned xb_add(unsigned* p, unsigned v) { return __hip_atomic_fetch_add(p, v, __ATOMIC_RELAXED, __HIP_MEMORY_SCOPE_AGENT); }
; #define XB_SPIN(cond, bar) do { unsigned _sp = 0; while (cond) { __builtin_amdgcn_s_sleep(1); \
;     if ((++_sp & 255u) == 0u) { if (xb_ld(&(bar)[XB_TMO])) break; if (_sp > XB_SPIN_CAP) { atomicAdd(&(bar)[XB_TMO], 1u); break; } } } } while (0)
; __device__ __forceinline__ void xcd_barrier(const XcdBarrier& b) {
;     asm volatile("s_waitcnt vmcnt(0)" ::: "memory");
;     __syncthreads();
;     if (threadIdx.x == 0) {
;         unsigned* bar = b.bar;
;         __builtin_amdgcn_s_waitcnt(0);
;         unsigned nloc = b.st[0], nx = b.st[1];
;         if (nloc == 0u) { xcd_barrier_complete(bar, b.x, nloc, nx); b.st[0] = nloc; b.st[1] = nx; }
;         const unsigned old = xb_add(&bar[XB_XSUB(b.x)], 1u);
;         const unsigned gen = old / nloc;
;         if (old + 1u == (gen + 1u) * nloc) {
;             __builtin_amdgcn_fence(__ATOMIC_RELEASE, "agent");
;             asm volatile("s_waitcnt vmcnt(0)" ::: "memory");
;             const unsigned og = xb_add(&bar[XB_TOP], 1u);
;             const unsigned tg = og / nx;
;             if (og + 1u == (tg + 1u) * nx) xb_add(&bar[XB_TOPGEN], 1u);
;             else XB_SPIN(xb_ld(&bar[XB_TOPGEN]) == tg, bar);
;             __builtin_amdgcn_fence(__ATOMIC_ACQUIRE, "agent");
;             xb_add(&bar[XB_XGEN(b.x)], 1u);
;             asm volatile("s_waitcnt vmcnt(0)" ::: "memory");
.LBB0_207:
	s_getreg_b32 s2, hwreg(HW_REG_XCC_ID, 0, 4)
	s_waitcnt vmcnt(0)
	s_barrier
	s_mov_b64 s[0:1], exec
	v_readlane_b32 s4, v253, 2
	v_readlane_b32 s5, v253, 3
	s_and_b64 s[4:5], s[0:1], s[4:5]
	s_mov_b64 exec, s[4:5]
	s_cbranch_execz .LBB0_259
	v_mov_b32_e32 v0, 0x20020
	s_waitcnt vmcnt(0) lgkmcnt(0)
	ds_read2_b32 v[2:3], v0 offset1:1
	s_and_b32 s3, s2, 15
	s_lshl_b32 s3, s3, 8
	s_add_u32 s6, s78, 0x1701400
	s_addc_u32 s7, s79, 0
	s_add_u32 s6, s6, s3
	s_addc_u32 s7, s7, 0
	s_add_u32 s10, s78, 0x1703c00
	s_addc_u32 s11, s79, 0
	s_lshr_b32 s3, s3, 1
	s_add_u32 s8, s10, s3
	s_addc_u32 s9, s11, 0
	global_atomic_add v0, v173, v212, s[6:7] sc0
	buffer_inv sc1
	s_waitcnt lgkmcnt(0)
	v_readfirstlane_b32 s30, v2
	v_readfirstlane_b32 s31, v3
	s_nop 3
	s_cmp_eq_u32 s30, 0
	s_cbranch_scc1 .Lxb_slow_n
	s_lshl_b32 s29, s66, 2
	s_add_i32 s29, s29, 1
	s_add_i32 s32, s29, 1
	s_mul_i32 s5, s32, s30
	s_mul_i32 s32, s32, s31
	s_waitcnt vmcnt(1)
	v_readfirstlane_b32 s3, v0
	s_nop 3
	s_add_i32 s3, s3, 1
	s_cmp_lg_u32 s3, s5
	s_cbranch_scc1 .Lxb_local_n
	global_atomic_add v173, v212, s[10:11] offset:0
	global_atomic_add v173, v212, s[10:11] offset:128
	global_atomic_add v173, v212, s[10:11] offset:256
	global_atomic_add v173, v212, s[10:11] offset:384
	global_atomic_add v173, v212, s[10:11] offset:512
	global_atomic_add v173, v212, s[10:11] offset:640
	global_atomic_add v173, v212, s[10:11] offset:768
	global_atomic_add v173, v212, s[10:11] offset:896

; __device__ __forceinline__ unsigned xb_ld(unsigned* p)              { return __hip_atomic_load(p, __ATOMIC_RELAXED, __HIP_MEMORY_SCOPE_AGENT); }
; __device__ __forceinline__ unsigned xb_add(unsigned* p, unsigned v) { return __hip_atomic_fetch_add(p, v, __ATOMIC_RELAXED, __HIP_MEMORY_SCOPE_AGENT); }
; #define XB_SPIN(cond, bar) do { unsigned _sp = 0; while (cond) { __builtin_amdgcn_s_sleep(1); \
;     if ((++_sp & 255u) == 0u) { if (xb_ld(&(bar)[XB_TMO])) break; if (_sp > XB_SPIN_CAP) { atomicAdd(&(bar)[XB_TMO], 1u); break; } } } } while (0)
; __device__ __forceinline__ void xcd_barrier(const XcdBarrier& b) {
;     asm volatile("s_waitcnt vmcnt(0)" ::: "memory");
;     __syncthreads();
;     if (threadIdx.x == 0) {
;         unsigned* bar = b.bar;
;         __builtin_amdgcn_s_waitcnt(0);
;         unsigned nloc = b.st[0], nx = b.st[1];
;         if (nloc == 0u) { xcd_barrier_complete(bar, b.x, nloc, nx); b.st[0] = nloc; b.st[1] = nx; }
;         const unsigned old = xb_add(&bar[XB_XSUB(b.x)], 1u);
;         const unsigned gen = old / nloc;
;         if (old + 1u == (gen + 1u) * nloc) {
;             __builtin_amdgcn_fence(__ATOMIC_RELEASE, "agent");
;             asm volatile("s_waitcnt vmcnt(0)" ::: "memory");
;             const unsigned og = xb_add(&bar[XB_TOP], 1u);
;             const unsigned tg = og / nx;
;             if (og + 1u == (tg + 1u) * nx) xb_add(&bar[XB_TOPGEN], 1u);
;             else XB_SPIN(xb_ld(&bar[XB_TOPGEN]) == tg, bar);
;             __builtin_amdgcn_fence(__ATOMIC_ACQUIRE, "agent");
;             xb_add(&bar[XB_XGEN(b.x)], 1u);
;             asm volatile("s_waitcnt vmcnt(0)" ::: "memory");
.LBB0_386:
	s_getreg_b32 s2, hwreg(HW_REG_XCC_ID, 0, 4)
	s_waitcnt vmcnt(0)
	v_writelane_b32 v255, s0, 13
	s_waitcnt vmcnt(0)
	s_barrier
	v_writelane_b32 v255, s1, 14
	s_mov_b64 s[0:1], exec
	v_readlane_b32 s4, v253, 2
	v_readlane_b32 s5, v253, 3
	s_and_b64 s[4:5], s[0:1], s[4:5]
	s_mov_b64 exec, s[4:5]
	s_cbranch_execz .LBB0_439
	v_mov_b32_e32 v0, 0x20020
	s_waitcnt vmcnt(0) lgkmcnt(0)
	ds_read2_b32 v[2:3], v0 offset1:1
	s_and_b32 s3, s2, 15
	s_lshl_b32 s3, s3, 8
	s_add_u32 s6, s78, 0x1701400
	s_addc_u32 s7, s79, 0
	s_add_u32 s6, s6, s3
	s_addc_u32 s7, s7, 0
	s_add_u32 s10, s78, 0x1703c00
	s_addc_u32 s11, s79, 0
	s_lshr_b32 s3, s3, 1
	s_add_u32 s8, s10, s3
	s_addc_u32 s9, s11, 0
	global_atomic_add v0, v173, v212, s[6:7] sc0
	buffer_inv sc1
	s_waitcnt lgkmcnt(0)
	v_readfirstlane_b32 s30, v2
	v_readfirstlane_b32 s31, v3
	s_nop 3
	s_cmp_eq_u32 s30, 0
	s_cbranch_scc1 .Lxb_slow_i
	s_lshl_b32 s29, s66, 2
	s_add_i32 s29, s29, 2
	s_add_i32 s32, s29, 1
	s_mul_i32 s5, s32, s30
	s_mul_i32 s32, s32, s31
	s_waitcnt vmcnt(1)
	v_readfirstlane_b32 s3, v0
	s_nop 3
	s_add_i32 s3, s3, 1
	s_cmp_lg_u32 s3, s5
	s_cbranch_scc1 .Lxb_local_i
	buffer_wbl2 sc1
	s_waitcnt vmcnt(0)
	global_atomic_add v173, v212, s[10:11] offset:0
	global_atomic_add v173, v212, s[10:11] offset:128
	global_atomic_add v173, v212, s[10:11] offset:256
	global_atomic_add v173, v212, s[10:11] offset:384
	global_atomic_add v173, v212, s[10:11] offset:512
	global_atomic_add v173, v212, s[10:11] offset:640
	global_atomic_add v173, v212, s[10:11] offset:768
	global_atomic_add v173, v212, s[10:11] offset:896

; __device__ __forceinline__ unsigned xb_ld(unsigned* p)              { return __hip_atomic_load(p, __ATOMIC_RELAXED, __HIP_MEMORY_SCOPE_AGENT); }
; __device__ __forceinline__ unsigned xb_add(unsigned* p, unsigned v) { return __hip_atomic_fetch_add(p, v, __ATOMIC_RELAXED, __HIP_MEMORY_SCOPE_AGENT); }
; #define XB_SPIN(cond, bar) do { unsigned _sp = 0; while (cond) { __builtin_amdgcn_s_sleep(1); \
;     if ((++_sp & 255u) == 0u) { if (xb_ld(&(bar)[XB_TMO])) break; if (_sp > XB_SPIN_CAP) { atomicAdd(&(bar)[XB_TMO], 1u); break; } } } } while (0)
; __device__ __forceinline__ void xcd_barrier(const XcdBarrier& b) {
;     asm volatile("s_waitcnt vmcnt(0)" ::: "memory");
;     __syncthreads();
;     if (threadIdx.x == 0) {
;         unsigned* bar = b.bar;
;         __builtin_amdgcn_s_waitcnt(0);
;         unsigned nloc = b.st[0], nx = b.st[1];
;         if (nloc == 0u) { xcd_barrier_complete(bar, b.x, nloc, nx); b.st[0] = nloc; b.st[1] = nx; }
;         const unsigned old = xb_add(&bar[XB_XSUB(b.x)], 1u);
;         const unsigned gen = old / nloc;
;         if (old + 1u == (gen + 1u) * nloc) {
;             __builtin_amdgcn_fence(__ATOMIC_RELEASE, "agent");
;             asm volatile("s_waitcnt vmcnt(0)" ::: "memory");
;             const unsigned og = xb_add(&bar[XB_TOP], 1u);
;             const unsigned tg = og / nx;
;             if (og + 1u == (tg + 1u) * nx) xb_add(&bar[XB_TOPGEN], 1u);
;             else XB_SPIN(xb_ld(&bar[XB_TOPGEN]) == tg, bar);
;             __builtin_amdgcn_fence(__ATOMIC_ACQUIRE, "agent");
;             xb_add(&bar[XB_XGEN(b.x)], 1u);
;             asm volatile("s_waitcnt vmcnt(0)" ::: "memory");
.LBB0_534:
	s_and_b64 vcc, exec, s[0:1]
	s_mov_b32 s93, s4
	s_cbranch_vccz .LBB0_441
	s_getreg_b32 s2, hwreg(HW_REG_XCC_ID, 0, 4)
	s_waitcnt vmcnt(0)
	s_barrier
	s_mov_b64 s[0:1], exec
	v_readlane_b32 s4, v253, 2
	v_readlane_b32 s5, v253, 3
	v_readlane_b32 s72, v254, 48
	v_readlane_b32 s80, v254, 50
	v_readlane_b32 s82, v254, 52
	v_readlane_b32 s92, v254, 54
	v_readlane_b32 s94, v254, 56
	v_readlane_b32 s98, v254, 58
	v_readlane_b32 s54, v254, 60
	v_readlane_b32 s56, v254, 62
	v_readlane_b32 s60, v255, 0
	v_readlane_b32 s62, v255, 2
	v_readlane_b32 s22, v255, 21
	s_and_b64 s[4:5], s[0:1], s[4:5]
	v_readlane_b32 s73, v254, 49
	v_readlane_b32 s81, v254, 51
	v_readlane_b32 s83, v254, 53
	v_readlane_b32 s93, v254, 55
	v_readlane_b32 s95, v254, 57
	v_readlane_b32 s99, v254, 59
	v_readlane_b32 s55, v254, 61
	v_readlane_b32 s57, v254, 63
	v_readlane_b32 s61, v255, 1
	v_readlane_b32 s63, v255, 3
	v_readlane_b32 s33, v255, 4
	v_readlane_b32 s85, v255, 5
	v_readlane_b32 s25, v254, 41
	v_readlane_b32 s28, v254, 43
	v_readlane_b32 s23, v255, 22
	s_mov_b64 exec, s[4:5]
	s_cbranch_execz .LBB0_587
	v_mov_b32_e32 v0, 0x20020
	s_waitcnt vmcnt(0) lgkmcnt(0)
	ds_read2_b32 v[2:3], v0 offset1:1
	s_and_b32 s3, s2, 15
	s_lshl_b32 s3, s3, 8
	s_add_u32 s6, s78, 0x1701400
	s_addc_u32 s7, s79, 0
	s_add_u32 s6, s6, s3
	s_addc_u32 s7, s7, 0
	s_add_u32 s10, s78, 0x1703c00
	s_addc_u32 s11, s79, 0
	s_lshr_b32 s3, s3, 1
	s_add_u32 s8, s10, s3
	s_addc_u32 s9, s11, 0
	global_atomic_add v0, v173, v212, s[6:7] sc0
	buffer_inv sc1
	s_waitcnt lgkmcnt(0)
	v_readfirstlane_b32 s30, v2
	v_readfirstlane_b32 s31, v3
	s_nop 3
	s_cmp_eq_u32 s30, 0
	s_cbranch_scc1 .Lxb_slow_m
	v_readlane_b32 s29, v255, 21
	s_nop 3
	s_lshl_b32 s29, s29, 2
	s_add_i32 s29, s29, 3
	s_add_i32 s32, s29, 1
	s_mul_i32 s5, s32, s30
	s_mul_i32 s32, s32, s31
	s_waitcnt vmcnt(1)
	v_readfirstlane_b32 s3, v0
	s_nop 3
	s_add_i32 s3, s3, 1
	s_cmp_lg_u32 s3, s5
	s_cbranch_scc1 .Lxb_local_m
	buffer_wbl2 sc1
	s_waitcnt vmcnt(0)
	global_atomic_add v173, v212, s[10:11] offset:0
	global_atomic_add v173, v212, s[10:11] offset:128
	global_atomic_add v173, v212, s[10:11] offset:256
	global_atomic_add v173, v212, s[10:11] offset:384
	global_atomic_add v173, v212, s[10:11] offset:512
	global_atomic_add v173, v212, s[10:11] offset:640
	global_atomic_add v173, v212, s[10:11] offset:768
	global_atomic_add v173, v212, s[10:11] offset:896

; __device__ __forceinline__ unsigned xb_ld(unsigned* p)              { return __hip_atomic_load(p, __ATOMIC_RELAXED, __HIP_MEMORY_SCOPE_AGENT); }
; __device__ __forceinline__ unsigned xb_add(unsigned* p, unsigned v) { return __hip_atomic_fetch_add(p, v, __ATOMIC_RELAXED, __HIP_MEMORY_SCOPE_AGENT); }
; #define XB_SPIN(cond, bar) do { unsigned _sp = 0; while (cond) { __builtin_amdgcn_s_sleep(1); \
;     if ((++_sp & 255u) == 0u) { if (xb_ld(&(bar)[XB_TMO])) break; if (_sp > XB_SPIN_CAP) { atomicAdd(&(bar)[XB_TMO], 1u); break; } } } } while (0)
; __device__ __forceinline__ void xcd_barrier(const XcdBarrier& b) {
;     asm volatile("s_waitcnt vmcnt(0)" ::: "memory");
;     __syncthreads();
;     if (threadIdx.x == 0) {
;         unsigned* bar = b.bar;
;         __builtin_amdgcn_s_waitcnt(0);
;         unsigned nloc = b.st[0], nx = b.st[1];
;         if (nloc == 0u) { xcd_barrier_complete(bar, b.x, nloc, nx); b.st[0] = nloc; b.st[1] = nx; }
;         const unsigned old = xb_add(&bar[XB_XSUB(b.x)], 1u);
;         const unsigned gen = old / nloc;
;         if (old + 1u == (gen + 1u) * nloc) {
;             __builtin_amdgcn_fence(__ATOMIC_RELEASE, "agent");
;             asm volatile("s_waitcnt vmcnt(0)" ::: "memory");
;             const unsigned og = xb_add(&bar[XB_TOP], 1u);
;             const unsigned tg = og / nx;
;             if (og + 1u == (tg + 1u) * nx) xb_add(&bar[XB_TOPGEN], 1u);
;             else XB_SPIN(xb_ld(&bar[XB_TOPGEN]) == tg, bar);
;             __builtin_amdgcn_fence(__ATOMIC_ACQUIRE, "agent");
;             xb_add(&bar[XB_XGEN(b.x)], 1u);
;             asm volatile("s_waitcnt vmcnt(0)" ::: "memory");
.LBB0_683:
	v_readlane_b32 s2, v255, 11
	v_readlane_b32 s3, v255, 12
	s_mov_b64 s[0:1], -1
	s_and_b64 vcc, exec, s[2:3]
	v_readlane_b32 s12, v255, 6
	s_mov_b64 s[26:27], 0x1000
	v_readlane_b32 s13, v255, 7
	s_cbranch_vccz .LBB0_190
	s_getreg_b32 s2, hwreg(HW_REG_XCC_ID, 0, 4)
	s_waitcnt vmcnt(0)
	s_barrier
	s_mov_b64 s[0:1], exec
	v_readlane_b32 s4, v253, 2
	v_readlane_b32 s5, v253, 3
	s_and_b64 s[4:5], s[0:1], s[4:5]
	s_mov_b64 exec, s[4:5]
	s_cbranch_execz .LBB0_189
	v_mov_b32_e32 v0, 0x20020
	s_waitcnt vmcnt(0) lgkmcnt(0)
	ds_read2_b32 v[2:3], v0 offset1:1
	s_and_b32 s3, s2, 15
	s_lshl_b32 s3, s3, 8
	s_add_u32 s6, s78, 0x1701400
	s_addc_u32 s7, s79, 0
	s_add_u32 s6, s6, s3
	s_addc_u32 s7, s7, 0
	s_add_u32 s10, s78, 0x1703c00
	s_addc_u32 s11, s79, 0
	s_lshr_b32 s3, s3, 1
	s_add_u32 s8, s10, s3
	s_addc_u32 s9, s11, 0
	global_atomic_add v0, v173, v212, s[6:7] sc0
	buffer_inv sc1
	s_waitcnt lgkmcnt(0)
	v_readfirstlane_b32 s30, v2
	v_readfirstlane_b32 s31, v3
	s_nop 3
	s_cmp_eq_u32 s30, 0
	s_cbranch_scc1 .Lxb_slow_o
	s_mov_b32 s29, 4
	s_add_i32 s32, s29, 1
	s_mul_i32 s5, s32, s30
	s_mul_i32 s32, s32, s31
	s_waitcnt vmcnt(1)
	v_readfirstlane_b32 s3, v0
	s_nop 3
	s_add_i32 s3, s3, 1
	s_cmp_lg_u32 s3, s5
	s_cbranch_scc1 .Lxb_local_o
	global_atomic_add v173, v212, s[10:11] offset:0
	global_atomic_add v173, v212, s[10:11] offset:128
	global_atomic_add v173, v212, s[10:11] offset:256
	global_atomic_add v173, v212, s[10:11] offset:384
	global_atomic_add v173, v212, s[10:11] offset:512
	global_atomic_add v173, v212, s[10:11] offset:640
	global_atomic_add v173, v212, s[10:11] offset:768
	global_atomic_add v173, v212, s[10:11] offset:896
